# P1/P12 tail weight-conversion loops: lane guards dropped (shapes are multiples of 64), gain loads issued with the tile loads, LDS read->cvt chain pipelined, loop 2 continues loop 1's item index
# baseline (speedup 1.0000x reference)
; #define LAS __attribute__((address_space(3)))
; #define INP(i) ((const float*)ldptr(ptab, (i)))
; __global__ void __launch_bounds__(512, 2) fwd_mega(Args args) {
;     ...
;             { const int first = (ph == 1) ? 144 : 128;
;               if (G == 256 && bx >= first) { __syncthreads(); LAS float* scr = (LAS float*)(lds + wave * 17664);
;                   for (int it = (bx - first) * 8 + wave; it < 88 * 32; it += (256 - first) * 8) p0_tr(ph == 1 ? INP(5) : INP(25), DFF, DM, ph == 1 ? Wd1 : Wd2, 128, 0, scr, it, lane);
;                   if (ph == 1) for (int it = (bx - first) * 8 + wave; it < 32 * 88; it += (256 - first) * 8) p0_tr(INP(23), DM, DFF, Wgu2, 256, 0, scr, it, lane, INP(22)); }
.LBB0_362:
	s_cmp_lt_i32 s2, s14
	v_readlane_b32 s16, v253, 4
	s_cselect_b64 s[12:13], -1, 0
	v_readlane_b32 s17, v253, 5
	s_or_b64 s[16:17], s[16:17], s[12:13]
	s_mov_b64 s[12:13], -1
	s_and_b64 vcc, exec, s[16:17]
	s_cbranch_vccnz .LBB0_472
	v_readlane_b32 s12, v255, 51
	s_mul_i32 s0, s12, 0x4500
	s_add_i32 s15, s0, 0
	s_sub_i32 s0, s2, s14
	s_lshl_b32 s0, s0, 3
	s_add_i32 s0, s0, s12
	s_mov_b32 s17, s0
	s_cmpk_lt_i32 s0, 0xb00
	s_cselect_b64 s[12:13], -1, 0
	s_cmpk_gt_i32 s0, 0xaff
	s_waitcnt vmcnt(0) lgkmcnt(0)
	s_barrier
	s_cbranch_scc1 .LBB0_418
	v_lshlrev_b32_e32 v0, 2, v154
	v_lshrrev_b32_e32 v65, 4, v154
	v_and_b32_e32 v64, 60, v0
	v_and_b32_e32 v3, 7, v238
	v_lshrrev_b32_e32 v72, 3, v154
	v_lshl_add_u32 v1, v64, 2, s15
	v_mul_u32_u24_e32 v2, 0x114, v65
	v_lshlrev_b32_e32 v0, 3, v3
	v_mul_u32_u24_e32 v3, 0x8a0, v3
	v_lshlrev_b32_e32 v4, 2, v72
	v_add3_u32 v73, s15, v3, v4
	v_or_b32_e32 v74, 8, v72
	v_or_b32_e32 v75, 16, v72
	v_or_b32_e32 v76, 24, v72
	v_or_b32_e32 v77, 32, v72
	v_or_b32_e32 v78, 40, v72
	v_or_b32_e32 v79, 48, v72
	v_or_b32_e32 v80, 56, v72
	s_lshl_b32 s16, s14, 3
	v_add_u32_e32 v81, v1, v2
	v_lshlrev_b32_e32 v66, 1, v0
	s_mov_b32 s17, s0
	s_branch .LBB0_366
.LBB0_365:
	s_waitcnt lgkmcnt(0)
	s_sub_i32 s22, s17, s16
	s_add_i32 s17, s22, 0x800
	s_cmpk_gt_i32 s22, 0x2ff
	s_cbranch_scc1 .LBB0_418

; #define LAS __attribute__((address_space(3)))
; __device__ __forceinline__ void p0_tr(const float* __restrict__ W, int K, int N, bf16* WT, int rstride, int roff, LAS float* scr, int item, int lane, const float* gk = nullptr) {
;     const int nblk = (N + 63) / 64, kb = item / nblk, nb = item % nblk, k0 = 64 * kb, n0 = 64 * nb;
;     const int kq = lane >> 4, n4 = (lane & 15) * 4;
;     const bool ok = (n0 + n4) < N;
;     f32x4 v[16];
; #pragma unroll
;     for (int i = 0; i < 16; ++i) v[i] = ok ? __builtin_nontemporal_load((const f32x4*)(W + (size_t)(k0 + 4 * i + kq) * N + n0 + n4)) : (f32x4){0.f, 0.f, 0.f, 0.f};
; #pragma unroll
;     for (int i = 0; i < 16; ++i)
; #pragma unroll
;         for (int e = 0; e < 4; ++e) scr[(4 * i + kq) * 69 + n4 + e] = v[i][e];
.LBB0_370:
	s_ashr_i32 s22, s17, 31
	s_lshr_b32 s22, s22, 27
	s_add_i32 s22, s17, s22
	s_and_b32 s23, s22, 0x3ffffe0
	s_sub_i32 s23, s17, s23
	s_lshl_b32 s28, s23, 6
	s_lshl_b32 s22, s22, 1
	s_ashr_i32 s29, s28, 31
	s_and_b32 s38, s22, 0xffffffc0
	s_lshl_b64 s[22:23], s[28:29], 2
	s_add_u32 s22, s40, s22
	v_or_b32_e32 v0, s28, v64
	s_addc_u32 s23, s41, s23
	v_lshlrev_b32_e32 v152, 2, v64
	v_cmp_gt_i32_e32 vcc, s89, v0
	v_or_b32_e32 v68, s38, v65
	v_lshl_add_u64 v[70:71], s[22:23], 0, v[152:153]
	v_ashrrev_i32_e32 v69, 31, v68
	v_lshlrev_b64 v[2:3], 13, v[68:69]
	v_lshl_add_u64 v[2:3], v[70:71], 0, v[2:3]
	global_load_dwordx4 v[4:7], v[2:3], off nt
	v_or_b32_e32 v0, 4, v68
	v_ashrrev_i32_e32 v1, 31, v0
	v_lshlrev_b64 v[0:1], 13, v[0:1]
	v_lshl_add_u64 v[0:1], v[70:71], 0, v[0:1]
	global_load_dwordx4 v[0:3], v[0:1], off nt
	v_or_b32_e32 v10, 8, v68
	v_ashrrev_i32_e32 v11, 31, v10
	v_lshlrev_b64 v[10:11], 13, v[10:11]
	v_lshl_add_u64 v[10:11], v[70:71], 0, v[10:11]
	global_load_dwordx4 v[12:15], v[10:11], off nt
	v_or_b32_e32 v8, 12, v68
	v_ashrrev_i32_e32 v9, 31, v8
	v_lshlrev_b64 v[8:9], 13, v[8:9]
	v_lshl_add_u64 v[8:9], v[70:71], 0, v[8:9]
	global_load_dwordx4 v[8:11], v[8:9], off nt
	v_or_b32_e32 v18, 16, v68
	v_ashrrev_i32_e32 v19, 31, v18
	v_lshlrev_b64 v[18:19], 13, v[18:19]
	v_lshl_add_u64 v[18:19], v[70:71], 0, v[18:19]
	global_load_dwordx4 v[20:23], v[18:19], off nt
	v_or_b32_e32 v16, 20, v68
	v_ashrrev_i32_e32 v17, 31, v16
	v_lshlrev_b64 v[16:17], 13, v[16:17]
	v_lshl_add_u64 v[16:17], v[70:71], 0, v[16:17]
	global_load_dwordx4 v[16:19], v[16:17], off nt
	v_or_b32_e32 v26, 24, v68
	v_ashrrev_i32_e32 v27, 31, v26
	v_lshlrev_b64 v[26:27], 13, v[26:27]
	v_lshl_add_u64 v[26:27], v[70:71], 0, v[26:27]
	global_load_dwordx4 v[28:31], v[26:27], off nt
	v_or_b32_e32 v24, 28, v68
	v_ashrrev_i32_e32 v25, 31, v24
	v_lshlrev_b64 v[24:25], 13, v[24:25]
	v_lshl_add_u64 v[24:25], v[70:71], 0, v[24:25]
	global_load_dwordx4 v[24:27], v[24:25], off nt
	v_or_b32_e32 v34, 32, v68
	v_ashrrev_i32_e32 v35, 31, v34
	v_lshlrev_b64 v[34:35], 13, v[34:35]
	v_lshl_add_u64 v[34:35], v[70:71], 0, v[34:35]
	global_load_dwordx4 v[36:39], v[34:35], off nt
	v_or_b32_e32 v32, 36, v68
	v_ashrrev_i32_e32 v33, 31, v32
	v_lshlrev_b64 v[32:33], 13, v[32:33]
	v_lshl_add_u64 v[32:33], v[70:71], 0, v[32:33]
	global_load_dwordx4 v[32:35], v[32:33], off nt
	v_or_b32_e32 v42, 40, v68
	v_ashrrev_i32_e32 v43, 31, v42
	v_lshlrev_b64 v[42:43], 13, v[42:43]
	v_lshl_add_u64 v[42:43], v[70:71], 0, v[42:43]
	global_load_dwordx4 v[44:47], v[42:43], off nt
	v_or_b32_e32 v40, 44, v68
	v_ashrrev_i32_e32 v41, 31, v40
	v_lshlrev_b64 v[40:41], 13, v[40:41]
	v_lshl_add_u64 v[40:41], v[70:71], 0, v[40:41]
	global_load_dwordx4 v[40:43], v[40:41], off nt
	v_or_b32_e32 v50, 48, v68
	v_ashrrev_i32_e32 v51, 31, v50
	v_lshlrev_b64 v[50:51], 13, v[50:51]
	v_lshl_add_u64 v[50:51], v[70:71], 0, v[50:51]
	global_load_dwordx4 v[52:55], v[50:51], off nt
	v_or_b32_e32 v48, 52, v68
	v_ashrrev_i32_e32 v49, 31, v48
	v_lshlrev_b64 v[48:49], 13, v[48:49]
	v_lshl_add_u64 v[48:49], v[70:71], 0, v[48:49]
	global_load_dwordx4 v[48:51], v[48:49], off nt
	v_or_b32_e32 v58, 56, v68
	v_ashrrev_i32_e32 v59, 31, v58
	v_lshlrev_b64 v[58:59], 13, v[58:59]
	v_lshl_add_u64 v[58:59], v[70:71], 0, v[58:59]
	global_load_dwordx4 v[60:63], v[58:59], off nt
	v_or_b32_e32 v56, 60, v68
	v_ashrrev_i32_e32 v57, 31, v56
	v_lshlrev_b64 v[56:57], 13, v[56:57]
	v_lshl_add_u64 v[56:57], v[70:71], 0, v[56:57]
	global_load_dwordx4 v[56:59], v[56:57], off nt
	s_waitcnt vmcnt(0)
	ds_write2_b32 v81, v4, v5 offset1:1
	ds_write2_b32 v81, v6, v7 offset0:2 offset1:3
	v_add_u32_e32 v4, 0x450, v81
	ds_write2_b32 v4, v0, v1 offset1:1
	v_add_u32_e32 v0, 0x458, v81
	ds_write2_b32 v0, v2, v3 offset1:1
	v_add_u32_e32 v0, 0x8a0, v81
	ds_write2_b32 v0, v12, v13 offset1:1
	v_add_u32_e32 v0, 0x8a8, v81
	ds_write2_b32 v0, v14, v15 offset1:1
	v_add_u32_e32 v0, 0xcf0, v81
	ds_write2_b32 v0, v8, v9 offset1:1
	v_add_u32_e32 v0, 0xcf8, v81
	ds_write2_b32 v0, v10, v11 offset1:1
	v_add_u32_e32 v0, 0x1140, v81
	ds_write2_b32 v0, v20, v21 offset1:1
	v_add_u32_e32 v0, 0x1148, v81
	ds_write2_b32 v0, v22, v23 offset1:1
	v_add_u32_e32 v0, 0x1590, v81
	ds_write2_b32 v0, v16, v17 offset1:1
	v_add_u32_e32 v0, 0x1598, v81
	ds_write2_b32 v0, v18, v19 offset1:1
	v_add_u32_e32 v0, 0x19e0, v81
	ds_write2_b32 v0, v28, v29 offset1:1
	v_add_u32_e32 v0, 0x19e8, v81
	ds_write2_b32 v0, v30, v31 offset1:1
	v_add_u32_e32 v0, 0x1e30, v81
	ds_write2_b32 v0, v24, v25 offset1:1
	v_add_u32_e32 v0, 0x1e38, v81
	ds_write2_b32 v0, v26, v27 offset1:1
	v_add_u32_e32 v0, 0x2280, v81
	ds_write2_b32 v0, v36, v37 offset1:1
	v_add_u32_e32 v0, 0x2288, v81
	ds_write2_b32 v0, v38, v39 offset1:1
	v_add_u32_e32 v0, 0x26d0, v81
	ds_write2_b32 v0, v32, v33 offset1:1
	v_add_u32_e32 v0, 0x26d8, v81
	ds_write2_b32 v0, v34, v35 offset1:1
	v_add_u32_e32 v0, 0x2b20, v81
	ds_write2_b32 v0, v44, v45 offset1:1
	v_add_u32_e32 v0, 0x2b28, v81
	ds_write2_b32 v0, v46, v47 offset1:1
	v_add_u32_e32 v0, 0x2f70, v81
	ds_write2_b32 v0, v40, v41 offset1:1
	v_add_u32_e32 v0, 0x2f78, v81
	ds_write2_b32 v0, v42, v43 offset1:1
	v_add_u32_e32 v0, 0x33c0, v81
	ds_write2_b32 v0, v52, v53 offset1:1
	v_add_u32_e32 v0, 0x33c8, v81
	ds_write2_b32 v0, v54, v55 offset1:1
	v_add_u32_e32 v0, 0x3810, v81
	ds_write2_b32 v0, v48, v49 offset1:1
	v_add_u32_e32 v0, 0x3818, v81
	ds_write2_b32 v0, v50, v51 offset1:1
	v_add_u32_e32 v0, 0x3c60, v81
	ds_write2_b32 v0, v60, v61 offset1:1
	v_add_u32_e32 v0, 0x3c68, v81
	ds_write2_b32 v0, v62, v63 offset1:1
	v_add_u32_e32 v0, 0x40b0, v81
	ds_write2_b32 v0, v56, v57 offset1:1
	v_add_u32_e32 v0, 0x40b8, v81
	ds_write2_b32 v0, v58, v59 offset1:1
	s_add_u32 s26, s56, s36
	s_waitcnt lgkmcnt(0)
; #define LAS __attribute__((address_space(3)))
; __device__ __forceinline__ unsigned pk2(float lo, float hi) { return pg8::cvt_pk_bf16(lo, hi); }
; __device__ __forceinline__ void p0_tr(const float* __restrict__ W, int K, int N, bf16* WT, int rstride, int roff, LAS float* scr, int item, int lane, const float* gk = nullptr) {
;     ...
;     for (int j = 0; j < 8; ++j) { const int n = (lane >> 3) + 8 * j, gn = n0 + n; const LAS float* sp = scr + (8 * c) * 69 + n;
;         u32x4 o; o.x = pk2(sp[0 * 69] * ga[0], sp[1 * 69] * ga[1]); o.y = pk2(sp[2 * 69] * ga[2], sp[3 * 69] * ga[3]); o.z = pk2(sp[4 * 69] * gb[0], sp[5 * 69] * gb[1]); o.w = pk2(sp[6 * 69] * gb[2], sp[7 * 69] * gb[3]);
;         if (gn < N) { const int dr = (gn >> 7) * rstride + roff + (gn & 127); *(u32x4*)(WT + (size_t)dr * K + k0 + 8 * c) = o; } }
	s_addc_u32 s29, s57, s37
	s_ashr_i32 s39, s38, 31
	s_lshl_b64 s[22:23], s[38:39], 1
	ds_read2_b32 v[82:83], v73 offset1:69
	ds_read2_b32 v[84:85], v73 offset0:138 offset1:207
	s_add_u32 s22, s26, s22
	s_waitcnt lgkmcnt(1)
	v_cvt_pk_bf16_f32 v0, v82, v83
	v_add_u32_e32 v6, 0x400, v73
	ds_read2_b32 v[86:87], v6 offset0:20 offset1:89
	ds_read2_b32 v[88:89], v6 offset0:158 offset1:227
	ds_read2_b32 v[90:91], v73 offset0:8 offset1:77
	ds_read2_b32 v[92:93], v73 offset0:146 offset1:215
	ds_read2_b32 v[94:95], v6 offset0:28 offset1:97
	ds_read2_b32 v[96:97], v6 offset0:166 offset1:235
	ds_read2_b32 v[98:99], v73 offset0:16 offset1:85
	ds_read2_b32 v[100:101], v73 offset0:154 offset1:223
	ds_read2_b32 v[102:103], v6 offset0:36 offset1:105
	ds_read2_b32 v[108:109], v6 offset0:174 offset1:243
	ds_read2_b32 v[110:111], v73 offset0:24 offset1:93
	s_addc_u32 s23, s29, s23
	v_mov_b32_e32 v67, v153
	v_or_b32_e32 v7, s28, v72
	s_waitcnt lgkmcnt(11)
	v_cvt_pk_bf16_f32 v1, v84, v85
	ds_read2_b32 v[112:113], v73 offset0:162 offset1:231
	v_lshl_add_u64 v[4:5], s[22:23], 0, v[66:67]
	v_cmp_gt_i32_e32 vcc, s89, v7
	s_waitcnt lgkmcnt(11)
	v_cvt_pk_bf16_f32 v2, v86, v87
	ds_read2_b32 v[114:115], v6 offset0:44 offset1:113
	s_waitcnt lgkmcnt(11)
	v_cvt_pk_bf16_f32 v3, v88, v89
	ds_read2_b32 v[116:117], v6 offset0:182 offset1:251
	v_mul_lo_u32 v8, v7, s5
	v_ashrrev_i32_e32 v9, 31, v8
	v_lshl_add_u64 v[8:9], v[8:9], 1, v[4:5]
	global_store_dwordx4 v[8:9], v[0:3], off
	s_nop 1
	s_waitcnt lgkmcnt(11)
	v_cvt_pk_bf16_f32 v0, v90, v91
	ds_read2_b32 v[118:119], v73 offset0:32 offset1:101
	v_or_b32_e32 v7, s28, v74
	s_waitcnt lgkmcnt(11)
	v_cvt_pk_bf16_f32 v1, v92, v93
	ds_read2_b32 v[120:121], v73 offset0:170 offset1:239
	v_cmp_gt_i32_e32 vcc, s89, v7
	s_waitcnt lgkmcnt(11)
	v_cvt_pk_bf16_f32 v2, v94, v95
	ds_read2_b32 v[122:123], v6 offset0:52 offset1:121
	s_waitcnt lgkmcnt(11)
	v_cvt_pk_bf16_f32 v3, v96, v97
	v_mul_lo_u32 v8, v7, s5
	v_ashrrev_i32_e32 v9, 31, v8
	v_lshl_add_u64 v[8:9], v[8:9], 1, v[4:5]
	global_store_dwordx4 v[8:9], v[0:3], off
	s_nop 1
	s_waitcnt lgkmcnt(10)
	v_cvt_pk_bf16_f32 v0, v98, v99
	v_or_b32_e32 v7, s28, v75
	s_waitcnt lgkmcnt(9)
	v_cvt_pk_bf16_f32 v1, v100, v101
	v_cmp_gt_i32_e32 vcc, s89, v7
	s_waitcnt lgkmcnt(8)
	v_cvt_pk_bf16_f32 v2, v102, v103
	s_waitcnt lgkmcnt(7)
	v_cvt_pk_bf16_f32 v3, v108, v109
	v_mul_lo_u32 v8, v7, s5
	v_ashrrev_i32_e32 v9, 31, v8
	v_lshl_add_u64 v[8:9], v[8:9], 1, v[4:5]
	global_store_dwordx4 v[8:9], v[0:3], off
	s_nop 1
	s_waitcnt lgkmcnt(6)
	v_cvt_pk_bf16_f32 v0, v110, v111
	v_or_b32_e32 v7, s28, v76
	s_waitcnt lgkmcnt(5)
	v_cvt_pk_bf16_f32 v1, v112, v113
	v_cmp_gt_i32_e32 vcc, s89, v7
	s_waitcnt lgkmcnt(4)
	v_cvt_pk_bf16_f32 v2, v114, v115
	s_waitcnt lgkmcnt(3)
	v_cvt_pk_bf16_f32 v3, v116, v117
	v_mul_lo_u32 v8, v7, s5
	v_ashrrev_i32_e32 v9, 31, v8
	v_lshl_add_u64 v[8:9], v[8:9], 1, v[4:5]
	global_store_dwordx4 v[8:9], v[0:3], off
	s_nop 1
	s_waitcnt lgkmcnt(2)
	v_cvt_pk_bf16_f32 v0, v118, v119
	v_or_b32_e32 v8, s28, v77
	s_waitcnt lgkmcnt(1)
	v_cvt_pk_bf16_f32 v1, v120, v121
	v_add_u32_e32 v7, 0x600, v73
	ds_read2_b32 v[82:83], v7 offset0:62 offset1:131
	ds_read2_b32 v[84:85], v73 offset0:40 offset1:109
	ds_read2_b32 v[86:87], v73 offset0:178 offset1:247
	ds_read2_b32 v[88:89], v6 offset0:60 offset1:129
	ds_read2_b32 v[90:91], v7 offset0:70 offset1:139
	ds_read2_b32 v[92:93], v73 offset0:48 offset1:117
	ds_read2_b32 v[94:95], v73 offset0:186 offset1:255
	ds_read2_b32 v[96:97], v6 offset0:68 offset1:137
	ds_read2_b32 v[98:99], v7 offset0:78 offset1:147
	ds_read2_b32 v[100:101], v73 offset0:56 offset1:125
	v_cmp_gt_i32_e32 vcc, s89, v8
	s_waitcnt lgkmcnt(10)
	v_cvt_pk_bf16_f32 v2, v122, v123
	s_waitcnt lgkmcnt(9)
	v_cvt_pk_bf16_f32 v3, v82, v83
	v_mul_lo_u32 v8, v8, s5
	v_ashrrev_i32_e32 v9, 31, v8
	v_lshl_add_u64 v[8:9], v[8:9], 1, v[4:5]
	global_store_dwordx4 v[8:9], v[0:3], off
	s_nop 1
	s_waitcnt lgkmcnt(8)
	v_cvt_pk_bf16_f32 v0, v84, v85
	v_or_b32_e32 v8, s28, v78
	s_waitcnt lgkmcnt(7)
	v_cvt_pk_bf16_f32 v1, v86, v87
	v_cmp_gt_i32_e32 vcc, s89, v8
	s_waitcnt lgkmcnt(6)
	v_cvt_pk_bf16_f32 v2, v88, v89
	s_waitcnt lgkmcnt(5)
	v_cvt_pk_bf16_f32 v3, v90, v91
	v_mul_lo_u32 v8, v8, s5
	v_ashrrev_i32_e32 v9, 31, v8
	v_lshl_add_u64 v[8:9], v[8:9], 1, v[4:5]
	global_store_dwordx4 v[8:9], v[0:3], off
	s_nop 1
	s_waitcnt lgkmcnt(4)
	v_cvt_pk_bf16_f32 v0, v92, v93
	v_or_b32_e32 v8, s28, v79
	s_waitcnt lgkmcnt(3)
	v_cvt_pk_bf16_f32 v1, v94, v95
	v_cmp_gt_i32_e32 vcc, s89, v8
	s_waitcnt lgkmcnt(2)
	v_cvt_pk_bf16_f32 v2, v96, v97
	s_waitcnt lgkmcnt(1)
	v_cvt_pk_bf16_f32 v3, v98, v99
	v_mul_lo_u32 v8, v8, s5
	v_ashrrev_i32_e32 v9, 31, v8
	v_lshl_add_u64 v[8:9], v[8:9], 1, v[4:5]
	global_store_dwordx4 v[8:9], v[0:3], off
	s_nop 1
	v_add_u32_e32 v2, 0x200, v73
	ds_read2_b32 v[102:103], v2 offset0:66 offset1:135
	ds_read2_b32 v[108:109], v6 offset0:76 offset1:145
	ds_read2_b32 v[110:111], v7 offset0:86 offset1:155
	s_waitcnt lgkmcnt(3)
	v_cvt_pk_bf16_f32 v0, v100, v101
	s_waitcnt lgkmcnt(2)
	v_cvt_pk_bf16_f32 v1, v102, v103
	v_or_b32_e32 v6, s28, v80
	v_cmp_gt_i32_e32 vcc, s89, v6
	s_waitcnt lgkmcnt(1)
	v_cvt_pk_bf16_f32 v2, v108, v109
	s_waitcnt lgkmcnt(0)
	v_cvt_pk_bf16_f32 v3, v110, v111
	v_mul_lo_u32 v6, v6, s5
	v_ashrrev_i32_e32 v7, 31, v6
	v_lshl_add_u64 v[4:5], v[6:7], 1, v[4:5]
	global_store_dwordx4 v[4:5], v[0:3], off
	s_nop 1
	s_branch .LBB0_365
; #define LAS __attribute__((address_space(3)))
; #define LDS_WAIT() asm volatile("s_waitcnt lgkmcnt(0)" ::: "memory")
; #define INP(i) ((const float*)ldptr(ptab, (i)))
; __device__ __forceinline__ void p0_tr(const float* __restrict__ W, int K, int N, bf16* WT, int rstride, int roff, LAS float* scr, int item, int lane, const float* gk = nullptr) {
;     const int nblk = (N + 63) / 64, kb = item / nblk, nb = item % nblk, k0 = 64 * kb, n0 = 64 * nb;
;     const int kq = lane >> 4, n4 = (lane & 15) * 4;
;     const bool ok = (n0 + n4) < N;
;     f32x4 v[16];
; #pragma unroll
;     for (int i = 0; i < 16; ++i) v[i] = ok ? __builtin_nontemporal_load((const f32x4*)(W + (size_t)(k0 + 4 * i + kq) * N + n0 + n4)) : (f32x4){0.f, 0.f, 0.f, 0.f};
; #pragma unroll
;     for (int i = 0; i < 16; ++i)
; #pragma unroll
;         for (int e = 0; e < 4; ++e) scr[(4 * i + kq) * 69 + n4 + e] = v[i][e];
;     LDS_WAIT(); asm volatile("" ::: "memory");
;     const int c = lane & 7;
;     f32x4 ga = {1.f, 1.f, 1.f, 1.f}, gb = {1.f, 1.f, 1.f, 1.f};
;     if (gk) { ga = *(const f32x4*)(gk + k0 + 8 * c); gb = *(const f32x4*)(gk + k0 + 8 * c + 4); }
; __global__ void __launch_bounds__(512, 2) fwd_mega(Args args) {
;     ...
;                   if (ph == 1) for (int it = (bx - first) * 8 + wave; it < 32 * 88; it += (256 - first) * 8) p0_tr(INP(23), DM, DFF, Wgu2, 256, 0, scr, it, lane, INP(22)); }
.LBB0_418:
	s_and_b64 s[12:13], s[10:11], s[12:13]
	s_andn2_b64 vcc, exec, s[12:13]
	s_cbranch_vccnz .LBB0_471
	v_lshlrev_b32_e32 v0, 2, v154
	v_lshrrev_b32_e32 v65, 4, v154
	v_and_b32_e32 v64, 60, v0
	v_and_b32_e32 v3, 7, v238
	v_lshrrev_b32_e32 v70, 3, v154
	v_readlane_b32 s12, v255, 58
	v_lshl_add_u32 v1, v64, 2, s15
	v_mul_u32_u24_e32 v2, 0x114, v65
	v_lshlrev_b32_e32 v0, 3, v3
	v_mul_u32_u24_e32 v4, 0x8a0, v3
	v_lshlrev_b32_e32 v5, 2, v70
	v_lshlrev_b32_e32 v152, 4, v3
	v_readlane_b32 s13, v255, 59
	v_add3_u32 v71, s15, v4, v5
	v_or_b32_e32 v72, 8, v70
	v_or_b32_e32 v73, 16, v70
	v_or_b32_e32 v74, 24, v70
	v_or_b32_e32 v75, 32, v70
	v_or_b32_e32 v76, 40, v70
	v_or_b32_e32 v77, 48, v70
	v_or_b32_e32 v78, 56, v70
	s_lshl_b32 s14, s14, 3
	s_add_i32 s0, s17, 0xfffff500
	v_lshl_add_u64 v[66:67], s[12:13], 0, v[152:153]
	v_add_u32_e32 v79, v1, v2
	v_lshlrev_b32_e32 v80, 2, v0
	s_branch .LBB0_421
.LBB0_420:
	s_waitcnt lgkmcnt(0)
	s_sub_i32 s12, s0, s14
	s_add_i32 s0, s12, 0x800
	s_cmpk_gt_i32 s12, 0x2ff
	s_cbranch_scc1 .LBB0_471
.LBB0_421:
	v_readlane_b32 s12, v255, 27
	v_lshlrev_b32_e32 v152, 2, v64
	v_mov_b32_e32 v4, 0
	v_mov_b32_e32 v0, s12
	s_mul_hi_i32 s12, s0, 0x2e8ba2e9
	s_lshr_b32 s13, s12, 31
	s_ashr_i32 s12, s12, 4
	ds_read_b128 v[0:3], v0
	s_add_i32 s12, s12, s13
	s_mul_i32 s13, s12, 0x58
	s_sub_i32 s15, s0, s13
	s_lshl_b32 s28, s12, 6
	s_lshl_b32 s12, s15, 6
	s_ashr_i32 s13, s12, 31
	s_waitcnt lgkmcnt(0)
	v_readfirstlane_b32 s23, v2
	s_lshl_b64 s[16:17], s[12:13], 2
	v_readfirstlane_b32 s22, v3
	s_add_u32 s16, s23, s16
	v_readfirstlane_b32 s36, v0
	v_or_b32_e32 v0, s12, v64
	s_addc_u32 s17, s22, s17
	v_readfirstlane_b32 s37, v1
	v_cmp_gt_i32_e32 vcc, s5, v0
	v_or_b32_e32 v81, s28, v65
	v_lshl_add_u64 v[68:69], s[16:17], 0, v[152:153]
	s_ashr_i32 s29, s28, 31
	s_cmp_eq_u64 s[36:37], 0
	v_mov_b32_e32 v126, 1.0
	v_mov_b32_e32 v127, 1.0
	v_mov_b32_e32 v128, 1.0
	v_mov_b32_e32 v129, 1.0
	v_mov_b32_e32 v130, 1.0
	v_mov_b32_e32 v131, 1.0
	v_mov_b32_e32 v132, 1.0
	v_mov_b32_e32 v133, 1.0
	s_cbranch_scc1 .LBB0_455
	s_lshl_b64 s[22:23], s[28:29], 2
	s_add_u32 s22, s36, s22
	s_addc_u32 s23, s37, s23
	global_load_dwordx4 v[126:129], v80, s[22:23]
	global_load_dwordx4 v[130:133], v80, s[22:23] offset:16
.LBB0_455:
	v_mad_i64_i32 v[2:3], s[16:17], v81, s7, v[68:69]
	global_load_dwordx4 v[4:7], v[2:3], off nt
	v_or_b32_e32 v0, 4, v81
	v_mad_i64_i32 v[0:1], s[16:17], v0, s7, v[68:69]
	global_load_dwordx4 v[0:3], v[0:1], off nt
	v_or_b32_e32 v9, 8, v81
	v_mad_i64_i32 v[10:11], s[16:17], v9, s7, v[68:69]
	global_load_dwordx4 v[12:15], v[10:11], off nt
	v_or_b32_e32 v8, 12, v81
	v_mad_i64_i32 v[8:9], s[16:17], v8, s7, v[68:69]
	global_load_dwordx4 v[8:11], v[8:9], off nt
	v_or_b32_e32 v17, 16, v81
	v_mad_i64_i32 v[18:19], s[16:17], v17, s7, v[68:69]
	global_load_dwordx4 v[20:23], v[18:19], off nt
	v_or_b32_e32 v16, 20, v81
	v_mad_i64_i32 v[16:17], s[16:17], v16, s7, v[68:69]
	global_load_dwordx4 v[16:19], v[16:17], off nt
	v_or_b32_e32 v25, 24, v81
	v_mad_i64_i32 v[26:27], s[16:17], v25, s7, v[68:69]
	global_load_dwordx4 v[28:31], v[26:27], off nt
	v_or_b32_e32 v24, 28, v81
	v_mad_i64_i32 v[24:25], s[16:17], v24, s7, v[68:69]
	global_load_dwordx4 v[24:27], v[24:25], off nt
	v_or_b32_e32 v33, 32, v81
	v_mad_i64_i32 v[34:35], s[16:17], v33, s7, v[68:69]
	global_load_dwordx4 v[36:39], v[34:35], off nt
	v_or_b32_e32 v32, 36, v81
	v_mad_i64_i32 v[32:33], s[16:17], v32, s7, v[68:69]
	global_load_dwordx4 v[32:35], v[32:33], off nt
	v_or_b32_e32 v41, 40, v81
	v_mad_i64_i32 v[42:43], s[16:17], v41, s7, v[68:69]
	global_load_dwordx4 v[44:47], v[42:43], off nt
	v_or_b32_e32 v40, 44, v81
	v_mad_i64_i32 v[40:41], s[16:17], v40, s7, v[68:69]
	global_load_dwordx4 v[40:43], v[40:41], off nt
	v_or_b32_e32 v49, 48, v81
	v_mad_i64_i32 v[50:51], s[16:17], v49, s7, v[68:69]
	global_load_dwordx4 v[52:55], v[50:51], off nt
	v_or_b32_e32 v48, 52, v81
	v_mad_i64_i32 v[48:49], s[16:17], v48, s7, v[68:69]
	global_load_dwordx4 v[48:51], v[48:49], off nt
	v_or_b32_e32 v57, 56, v81
	v_mad_i64_i32 v[58:59], s[16:17], v57, s7, v[68:69]
	global_load_dwordx4 v[60:63], v[58:59], off nt
	v_or_b32_e32 v56, 60, v81
	v_mad_i64_i32 v[56:57], s[16:17], v56, s7, v[68:69]
	global_load_dwordx4 v[56:59], v[56:57], off nt
	s_waitcnt vmcnt(0)
	ds_write2_b32 v79, v4, v5 offset1:1
	ds_write2_b32 v79, v6, v7 offset0:2 offset1:3
	v_add_u32_e32 v4, 0x450, v79
	ds_write2_b32 v4, v0, v1 offset1:1
	v_add_u32_e32 v0, 0x458, v79
	ds_write2_b32 v0, v2, v3 offset1:1
	v_add_u32_e32 v0, 0x8a0, v79
	ds_write2_b32 v0, v12, v13 offset1:1
	v_add_u32_e32 v0, 0x8a8, v79
	ds_write2_b32 v0, v14, v15 offset1:1
	v_add_u32_e32 v0, 0xcf0, v79
	ds_write2_b32 v0, v8, v9 offset1:1
	v_add_u32_e32 v0, 0xcf8, v79
	ds_write2_b32 v0, v10, v11 offset1:1
	v_add_u32_e32 v0, 0x1140, v79
	ds_write2_b32 v0, v20, v21 offset1:1
	v_add_u32_e32 v0, 0x1148, v79
	ds_write2_b32 v0, v22, v23 offset1:1
	v_add_u32_e32 v0, 0x1590, v79
	ds_write2_b32 v0, v16, v17 offset1:1
	v_add_u32_e32 v0, 0x1598, v79
	ds_write2_b32 v0, v18, v19 offset1:1
	v_add_u32_e32 v0, 0x19e0, v79
	ds_write2_b32 v0, v28, v29 offset1:1
	v_add_u32_e32 v0, 0x19e8, v79
	ds_write2_b32 v0, v30, v31 offset1:1
	v_add_u32_e32 v0, 0x1e30, v79
	ds_write2_b32 v0, v24, v25 offset1:1
	v_add_u32_e32 v0, 0x1e38, v79
	ds_write2_b32 v0, v26, v27 offset1:1
	v_add_u32_e32 v0, 0x2280, v79
	ds_write2_b32 v0, v36, v37 offset1:1
	v_add_u32_e32 v0, 0x2288, v79
	ds_write2_b32 v0, v38, v39 offset1:1
	v_add_u32_e32 v0, 0x26d0, v79
	ds_write2_b32 v0, v32, v33 offset1:1
	v_add_u32_e32 v0, 0x26d8, v79
	ds_write2_b32 v0, v34, v35 offset1:1
	v_add_u32_e32 v0, 0x2b20, v79
	ds_write2_b32 v0, v44, v45 offset1:1
	v_add_u32_e32 v0, 0x2b28, v79
	ds_write2_b32 v0, v46, v47 offset1:1
	v_add_u32_e32 v0, 0x2f70, v79
	ds_write2_b32 v0, v40, v41 offset1:1
	v_add_u32_e32 v0, 0x2f78, v79
	ds_write2_b32 v0, v42, v43 offset1:1
	v_add_u32_e32 v0, 0x33c0, v79
	ds_write2_b32 v0, v52, v53 offset1:1
	v_add_u32_e32 v0, 0x33c8, v79
	ds_write2_b32 v0, v54, v55 offset1:1
	v_add_u32_e32 v0, 0x3810, v79
	ds_write2_b32 v0, v48, v49 offset1:1
	v_add_u32_e32 v0, 0x3818, v79
	ds_write2_b32 v0, v50, v51 offset1:1
	v_add_u32_e32 v0, 0x3c60, v79
	ds_write2_b32 v0, v60, v61 offset1:1
	v_add_u32_e32 v0, 0x3c68, v79
	ds_write2_b32 v0, v62, v63 offset1:1
	v_add_u32_e32 v0, 0x40b0, v79
	ds_write2_b32 v0, v56, v57 offset1:1
	v_add_u32_e32 v0, 0x40b8, v79
	ds_write2_b32 v0, v58, v59 offset1:1
	s_waitcnt lgkmcnt(0)
; #define LAS __attribute__((address_space(3)))
; __device__ __forceinline__ unsigned pk2(float lo, float hi) { return pg8::cvt_pk_bf16(lo, hi); }
; __device__ __forceinline__ void p0_tr(const float* __restrict__ W, int K, int N, bf16* WT, int rstride, int roff, LAS float* scr, int item, int lane, const float* gk = nullptr) {
;     ...
;     f32x4 ga = {1.f, 1.f, 1.f, 1.f}, gb = {1.f, 1.f, 1.f, 1.f};
;     if (gk) { ga = *(const f32x4*)(gk + k0 + 8 * c); gb = *(const f32x4*)(gk + k0 + 8 * c + 4); }
; #pragma unroll
;     for (int j = 0; j < 8; ++j) { const int n = (lane >> 3) + 8 * j, gn = n0 + n; const LAS float* sp = scr + (8 * c) * 69 + n;
;         u32x4 o; o.x = pk2(sp[0 * 69] * ga[0], sp[1 * 69] * ga[1]); o.y = pk2(sp[2 * 69] * ga[2], sp[3 * 69] * ga[3]); o.z = pk2(sp[4 * 69] * gb[0], sp[5 * 69] * gb[1]); o.w = pk2(sp[6 * 69] * gb[2], sp[7 * 69] * gb[3]);
;         if (gn < N) { const int dr = (gn >> 7) * rstride + roff + (gn & 127); *(u32x4*)(WT + (size_t)dr * K + k0 + 8 * c) = o; } }
	ds_read2_b32 v[82:83], v71 offset1:69
	ds_read2_b32 v[84:85], v71 offset0:138 offset1:207
	v_add_u32_e32 v14, 0x400, v71
	ds_read2_b32 v[86:87], v14 offset0:20 offset1:89
	ds_read2_b32 v[88:89], v14 offset0:158 offset1:227
	ds_read2_b32 v[90:91], v71 offset0:8 offset1:77
	ds_read2_b32 v[92:93], v71 offset0:146 offset1:215
	ds_read2_b32 v[94:95], v14 offset0:28 offset1:97
	ds_read2_b32 v[96:97], v14 offset0:166 offset1:235
	ds_read2_b32 v[98:99], v71 offset0:16 offset1:85
	ds_read2_b32 v[100:101], v71 offset0:154 offset1:223
	ds_read2_b32 v[102:103], v14 offset0:36 offset1:105
	ds_read2_b32 v[108:109], v14 offset0:174 offset1:243
	s_lshl_b32 s13, s15, 7
	v_or_b32_e32 v15, s12, v70
	v_lshl_add_u64 v[12:13], s[28:29], 1, v[66:67]
	s_waitcnt lgkmcnt(11)
	v_mul_f32_e32 v8, v126, v82
	v_mul_f32_e32 v9, v127, v83
	ds_read2_b32 v[110:111], v71 offset0:24 offset1:93
	v_cvt_pk_bf16_f32 v8, v8, v9
	s_and_b32 s15, s13, 0xffffff00
	v_cmp_gt_i32_e32 vcc, s5, v15
	s_waitcnt lgkmcnt(11)
	v_mul_f32_e32 v9, v128, v84
	v_mul_f32_e32 v10, v129, v85
	ds_read2_b32 v[112:113], v71 offset0:162 offset1:231
	v_cvt_pk_bf16_f32 v9, v9, v10
	s_waitcnt lgkmcnt(11)
	v_mul_f32_e32 v10, v130, v86
	v_mul_f32_e32 v11, v131, v87
	ds_read2_b32 v[114:115], v14 offset0:44 offset1:113
	v_cvt_pk_bf16_f32 v10, v10, v11
	s_waitcnt lgkmcnt(11)
	v_mul_f32_e32 v11, v132, v88
	v_mul_f32_e32 v16, v133, v89
	ds_read2_b32 v[116:117], v14 offset0:182 offset1:251
	v_cvt_pk_bf16_f32 v11, v11, v16
	v_and_b32_e32 v15, 0x47, v15
	v_or_b32_e32 v16, s15, v15
	v_ashrrev_i32_e32 v17, 31, v16
	v_lshlrev_b64 v[16:17], 12, v[16:17]
	v_lshl_add_u64 v[16:17], v[12:13], 0, v[16:17]
	global_store_dwordx4 v[16:17], v[8:11], off
	s_nop 1
	v_or_b32_e32 v15, s12, v72
	v_cmp_gt_i32_e32 vcc, s5, v15
	s_waitcnt lgkmcnt(11)
	v_mul_f32_e32 v8, v126, v90
	v_mul_f32_e32 v9, v127, v91
	ds_read2_b32 v[118:119], v71 offset0:32 offset1:101
	v_cvt_pk_bf16_f32 v8, v8, v9
	s_waitcnt lgkmcnt(11)
	v_mul_f32_e32 v9, v128, v92
	v_mul_f32_e32 v10, v129, v93
	ds_read2_b32 v[120:121], v71 offset0:170 offset1:239
	v_cvt_pk_bf16_f32 v9, v9, v10
	s_waitcnt lgkmcnt(11)
	v_mul_f32_e32 v10, v130, v94
	v_mul_f32_e32 v11, v131, v95
	ds_read2_b32 v[122:123], v14 offset0:52 offset1:121
	v_cvt_pk_bf16_f32 v10, v10, v11
	s_waitcnt lgkmcnt(11)
	v_mul_f32_e32 v11, v132, v96
	v_mul_f32_e32 v16, v133, v97
	v_cvt_pk_bf16_f32 v11, v11, v16
	v_and_b32_e32 v15, 0x4f, v15
	v_or_b32_e32 v16, s15, v15
	v_ashrrev_i32_e32 v17, 31, v16
	v_lshlrev_b64 v[16:17], 12, v[16:17]
	v_lshl_add_u64 v[16:17], v[12:13], 0, v[16:17]
	global_store_dwordx4 v[16:17], v[8:11], off
	s_nop 1
	v_or_b32_e32 v15, s12, v73
	v_cmp_gt_i32_e32 vcc, s5, v15
	s_waitcnt lgkmcnt(10)
	v_mul_f32_e32 v8, v126, v98
	v_mul_f32_e32 v9, v127, v99
	v_cvt_pk_bf16_f32 v8, v8, v9
	s_waitcnt lgkmcnt(9)
	v_mul_f32_e32 v9, v128, v100
	v_mul_f32_e32 v10, v129, v101
	v_cvt_pk_bf16_f32 v9, v9, v10
	s_waitcnt lgkmcnt(8)
	v_mul_f32_e32 v10, v130, v102
	v_mul_f32_e32 v11, v131, v103
	v_cvt_pk_bf16_f32 v10, v10, v11
	s_waitcnt lgkmcnt(7)
	v_mul_f32_e32 v11, v132, v108
	v_mul_f32_e32 v16, v133, v109
	v_cvt_pk_bf16_f32 v11, v11, v16
	v_and_b32_e32 v15, 0x57, v15
	v_or_b32_e32 v16, s15, v15
	v_ashrrev_i32_e32 v17, 31, v16
	v_lshlrev_b64 v[16:17], 12, v[16:17]
	v_lshl_add_u64 v[16:17], v[12:13], 0, v[16:17]
	global_store_dwordx4 v[16:17], v[8:11], off
	s_nop 1
	v_or_b32_e32 v15, s12, v74
	v_cmp_gt_i32_e32 vcc, s5, v15
	s_waitcnt lgkmcnt(6)
	v_mul_f32_e32 v8, v126, v110
	v_mul_f32_e32 v9, v127, v111
	v_cvt_pk_bf16_f32 v8, v8, v9
	s_waitcnt lgkmcnt(5)
	v_mul_f32_e32 v9, v128, v112
	v_mul_f32_e32 v10, v129, v113
	v_cvt_pk_bf16_f32 v9, v9, v10
	s_waitcnt lgkmcnt(4)
	v_mul_f32_e32 v10, v130, v114
	v_mul_f32_e32 v11, v131, v115
	v_cvt_pk_bf16_f32 v10, v10, v11
	s_waitcnt lgkmcnt(3)
; #define LAS __attribute__((address_space(3)))
; __device__ __forceinline__ unsigned pk2(float lo, float hi) { return pg8::cvt_pk_bf16(lo, hi); }
; __device__ __forceinline__ void p0_tr(const float* __restrict__ W, int K, int N, bf16* WT, int rstride, int roff, LAS float* scr, int item, int lane, const float* gk = nullptr) {
;     ...
;     for (int j = 0; j < 8; ++j) { const int n = (lane >> 3) + 8 * j, gn = n0 + n; const LAS float* sp = scr + (8 * c) * 69 + n;
;         u32x4 o; o.x = pk2(sp[0 * 69] * ga[0], sp[1 * 69] * ga[1]); o.y = pk2(sp[2 * 69] * ga[2], sp[3 * 69] * ga[3]); o.z = pk2(sp[4 * 69] * gb[0], sp[5 * 69] * gb[1]); o.w = pk2(sp[6 * 69] * gb[2], sp[7 * 69] * gb[3]);
;         if (gn < N) { const int dr = (gn >> 7) * rstride + roff + (gn & 127); *(u32x4*)(WT + (size_t)dr * K + k0 + 8 * c) = o; } }
	v_mul_f32_e32 v11, v132, v116
	v_mul_f32_e32 v16, v133, v117
	v_cvt_pk_bf16_f32 v11, v11, v16
	v_and_b32_e32 v15, 0x5f, v15
	v_or_b32_e32 v16, s15, v15
	v_ashrrev_i32_e32 v17, 31, v16
	v_lshlrev_b64 v[16:17], 12, v[16:17]
	v_lshl_add_u64 v[16:17], v[12:13], 0, v[16:17]
	global_store_dwordx4 v[16:17], v[8:11], off
	s_nop 1
	v_add_u32_e32 v15, 0x600, v71
	ds_read2_b32 v[82:83], v15 offset0:62 offset1:131
	ds_read2_b32 v[84:85], v71 offset0:40 offset1:109
	ds_read2_b32 v[86:87], v71 offset0:178 offset1:247
	ds_read2_b32 v[88:89], v14 offset0:60 offset1:129
	ds_read2_b32 v[90:91], v15 offset0:70 offset1:139
	ds_read2_b32 v[92:93], v71 offset0:48 offset1:117
	ds_read2_b32 v[94:95], v71 offset0:186 offset1:255
	ds_read2_b32 v[96:97], v14 offset0:68 offset1:137
	ds_read2_b32 v[98:99], v15 offset0:78 offset1:147
	v_or_b32_e32 v16, s12, v75
	v_cmp_gt_i32_e32 vcc, s5, v16
	s_waitcnt lgkmcnt(11)
	v_mul_f32_e32 v8, v126, v118
	v_mul_f32_e32 v9, v127, v119
	ds_read2_b32 v[100:101], v71 offset0:56 offset1:125
	v_cvt_pk_bf16_f32 v8, v8, v9
	s_waitcnt lgkmcnt(11)
	v_mul_f32_e32 v9, v128, v120
	v_mul_f32_e32 v10, v129, v121
	v_cvt_pk_bf16_f32 v9, v9, v10
	s_waitcnt lgkmcnt(10)
	v_mul_f32_e32 v10, v130, v122
	v_mul_f32_e32 v11, v131, v123
	v_cvt_pk_bf16_f32 v10, v10, v11
	s_waitcnt lgkmcnt(9)
	v_mul_f32_e32 v11, v132, v82
	v_mul_f32_e32 v17, v133, v83
	v_cvt_pk_bf16_f32 v11, v11, v17
	v_and_b32_e32 v16, 0x67, v16
	v_or_b32_e32 v16, s15, v16
	v_ashrrev_i32_e32 v17, 31, v16
	v_lshlrev_b64 v[16:17], 12, v[16:17]
	v_lshl_add_u64 v[16:17], v[12:13], 0, v[16:17]
	global_store_dwordx4 v[16:17], v[8:11], off
	s_nop 1
	v_or_b32_e32 v16, s12, v76
	v_cmp_gt_i32_e32 vcc, s5, v16
	s_waitcnt lgkmcnt(8)
	v_mul_f32_e32 v8, v126, v84
	v_mul_f32_e32 v9, v127, v85
	v_cvt_pk_bf16_f32 v8, v8, v9
	s_waitcnt lgkmcnt(7)
	v_mul_f32_e32 v9, v128, v86
	v_mul_f32_e32 v10, v129, v87
	v_cvt_pk_bf16_f32 v9, v9, v10
	s_waitcnt lgkmcnt(6)
	v_mul_f32_e32 v10, v130, v88
	v_mul_f32_e32 v11, v131, v89
	v_cvt_pk_bf16_f32 v10, v10, v11
	s_waitcnt lgkmcnt(5)
	v_mul_f32_e32 v11, v132, v90
	v_mul_f32_e32 v17, v133, v91
	v_cvt_pk_bf16_f32 v11, v11, v17
	v_and_b32_e32 v16, 0x6f, v16
	v_or_b32_e32 v16, s15, v16
	v_ashrrev_i32_e32 v17, 31, v16
	v_lshlrev_b64 v[16:17], 12, v[16:17]
	v_lshl_add_u64 v[16:17], v[12:13], 0, v[16:17]
	global_store_dwordx4 v[16:17], v[8:11], off
	s_nop 1
	v_or_b32_e32 v16, s12, v77
	v_cmp_gt_i32_e32 vcc, s5, v16
	s_waitcnt lgkmcnt(4)
	v_mul_f32_e32 v8, v126, v92
	v_mul_f32_e32 v9, v127, v93
	v_cvt_pk_bf16_f32 v8, v8, v9
	s_waitcnt lgkmcnt(3)
	v_mul_f32_e32 v9, v128, v94
	v_mul_f32_e32 v10, v129, v95
	v_cvt_pk_bf16_f32 v9, v9, v10
	s_waitcnt lgkmcnt(2)
	v_mul_f32_e32 v10, v130, v96
	v_mul_f32_e32 v11, v131, v97
	v_cvt_pk_bf16_f32 v10, v10, v11
	s_waitcnt lgkmcnt(1)
	v_mul_f32_e32 v11, v132, v98
	v_mul_f32_e32 v17, v133, v99
	v_cvt_pk_bf16_f32 v11, v11, v17
	v_and_b32_e32 v16, 0x77, v16
	v_or_b32_e32 v16, s15, v16
	v_ashrrev_i32_e32 v17, 31, v16
	v_lshlrev_b64 v[16:17], 12, v[16:17]
	v_lshl_add_u64 v[16:17], v[12:13], 0, v[16:17]
	global_store_dwordx4 v[16:17], v[8:11], off
	s_nop 1
	v_add_u32_e32 v10, 0x200, v71
	ds_read2_b32 v[102:103], v10 offset0:66 offset1:135
	ds_read2_b32 v[108:109], v14 offset0:76 offset1:145
	ds_read2_b32 v[110:111], v15 offset0:86 offset1:155
	s_waitcnt lgkmcnt(3)
	v_mul_f32_e32 v0, v126, v100
	v_mul_f32_e32 v1, v127, v101
	v_cvt_pk_bf16_f32 v0, v0, v1
	s_waitcnt lgkmcnt(2)
	v_mul_f32_e32 v1, v128, v102
	v_mul_f32_e32 v2, v129, v103
	v_cvt_pk_bf16_f32 v1, v1, v2
	s_waitcnt lgkmcnt(1)
	v_mul_f32_e32 v2, v130, v108
	v_mul_f32_e32 v3, v131, v109
	v_cvt_pk_bf16_f32 v2, v2, v3
	v_or_b32_e32 v4, s12, v78
	v_cmp_gt_i32_e32 vcc, s5, v4
	s_waitcnt lgkmcnt(0)
	v_mul_f32_e32 v3, v132, v110
	v_mul_f32_e32 v5, v133, v111
	v_cvt_pk_bf16_f32 v3, v3, v5
	v_and_b32_e32 v4, 0x7f, v4
	v_or_b32_e32 v4, s15, v4
	v_ashrrev_i32_e32 v5, 31, v4
	v_lshlrev_b64 v[4:5], 12, v[4:5]
	v_lshl_add_u64 v[4:5], v[12:13], 0, v[4:5]
	global_store_dwordx4 v[4:5], v[0:3], off
	s_nop 1
	s_branch .LBB0_420
